# prep phase adaLN GEMV: K loop regenerated with rolling 16-row prefetch (hipcc had one 512B load in flight per wave behind vmcnt(0))
# speedup vs baseline: 1.0559x; 1.0109x over previous
.LBB0_49:
	s_mul_hi_i32 s0, s16, 0x2aaaaaab
	s_lshr_b32 s1, s0, 31
	s_ashr_i32 s0, s0, 3
	s_add_i32 s4, s0, s1
	s_mul_i32 s0, s4, 48
	s_sub_i32 s0, s16, s0
	s_lshl_b32 s0, s0, 7
	s_ashr_i32 s1, s0, 31
	s_mul_i32 s7, s4, 0x1800000
	s_lshl_b64 s[2:3], s[0:1], 2
	s_mul_hi_i32 s6, s4, 0x1800000
	s_add_u32 s0, s7, s2
	s_addc_u32 s1, s6, s3
	v_mov_b32_e32 v32, 0
	v_lshl_add_u64 v[12:13], v[10:11], 0, s[0:1]
	s_mov_b64 s[6:7], 0
	v_mov_b32_e32 v35, v5
	v_mov_b32_e32 v30, 0
	v_mov_b32_e32 v28, 0
	v_mov_b32_e32 v26, 0
	v_mov_b32_e32 v24, 0
	v_mov_b32_e32 v22, 0
	v_mov_b32_e32 v20, 0
	v_mov_b32_e32 v18, 0
	v_mov_b32_e32 v16, 0
	v_mov_b32_e32 v33, v32
	v_mov_b32_e32 v31, v32
	v_mov_b32_e32 v29, v32
	v_mov_b32_e32 v27, v32
	v_mov_b32_e32 v25, v32
	v_mov_b32_e32 v23, v32
	v_mov_b32_e32 v21, v32
	v_mov_b32_e32 v19, v32
	v_mov_b32_e32 v17, v32
	s_mov_b32 s1, 0
	global_load_dwordx2 v[60:61], v[12:13], off
	s_mov_b32 s0, 0x6000
	v_lshl_add_u64 v[92:93], v[12:13], 0, s[0:1]
	global_load_dwordx2 v[62:63], v[92:93], off
	s_mov_b32 s0, 0xc000
	v_lshl_add_u64 v[92:93], v[12:13], 0, s[0:1]
	global_load_dwordx2 v[64:65], v[92:93], off
	s_mov_b32 s0, 0x12000
	v_lshl_add_u64 v[92:93], v[12:13], 0, s[0:1]
	global_load_dwordx2 v[66:67], v[92:93], off
	s_mov_b32 s0, 0x18000
	v_lshl_add_u64 v[92:93], v[12:13], 0, s[0:1]
	global_load_dwordx2 v[68:69], v[92:93], off
	s_mov_b32 s0, 0x1e000
	v_lshl_add_u64 v[92:93], v[12:13], 0, s[0:1]
	global_load_dwordx2 v[70:71], v[92:93], off
	s_mov_b32 s0, 0x24000
	v_lshl_add_u64 v[92:93], v[12:13], 0, s[0:1]
	global_load_dwordx2 v[72:73], v[92:93], off
	s_mov_b32 s0, 0x2a000
	v_lshl_add_u64 v[92:93], v[12:13], 0, s[0:1]
	global_load_dwordx2 v[74:75], v[92:93], off
	s_mov_b32 s0, 0x30000
	v_lshl_add_u64 v[92:93], v[12:13], 0, s[0:1]
	global_load_dwordx2 v[76:77], v[92:93], off
	s_mov_b32 s0, 0x36000
	v_lshl_add_u64 v[92:93], v[12:13], 0, s[0:1]
	global_load_dwordx2 v[78:79], v[92:93], off
	s_mov_b32 s0, 0x3c000
	v_lshl_add_u64 v[92:93], v[12:13], 0, s[0:1]
	global_load_dwordx2 v[80:81], v[92:93], off
	s_mov_b32 s0, 0x42000
	v_lshl_add_u64 v[92:93], v[12:13], 0, s[0:1]
	global_load_dwordx2 v[82:83], v[92:93], off
	s_mov_b32 s0, 0x48000
	v_lshl_add_u64 v[92:93], v[12:13], 0, s[0:1]
	global_load_dwordx2 v[84:85], v[92:93], off
	s_mov_b32 s0, 0x4e000
	v_lshl_add_u64 v[92:93], v[12:13], 0, s[0:1]
	global_load_dwordx2 v[86:87], v[92:93], off
	s_mov_b32 s0, 0x54000
	v_lshl_add_u64 v[92:93], v[12:13], 0, s[0:1]
	global_load_dwordx2 v[88:89], v[92:93], off
	s_mov_b32 s0, 0x5a000
	v_lshl_add_u64 v[92:93], v[12:13], 0, s[0:1]
	global_load_dwordx2 v[90:91], v[92:93], off
.LBB0_50:
	s_add_u32 s40, s6, 0x60000
	s_addc_u32 s41, s7, 0
	v_lshl_add_u64 v[94:95], v[12:13], 0, s[40:41]
	v_add_u32_e32 v40, 0x1000, v35
	v_add_u32_e32 v42, 0x2000, v35
	v_add_u32_e32 v44, 0x3000, v35
	v_add_u32_e32 v46, 0x4000, v35
	v_add_u32_e32 v48, 0x5000, v35
	v_add_u32_e32 v50, 0x6000, v35
	v_add_u32_e32 v52, 0x7000, v35
	v_add_u32_e32 v54, 0x8000, v35
	ds_read2_b32 v[38:39], v35 offset1:1
	ds_read2_b32 v[40:41], v40 offset1:1
	ds_read2_b32 v[42:43], v42 offset1:1
	ds_read2_b32 v[44:45], v44 offset1:1
	ds_read2_b32 v[46:47], v46 offset1:1
	ds_read2_b32 v[48:49], v48 offset1:1
	ds_read2_b32 v[50:51], v50 offset1:1
	ds_read2_b32 v[52:53], v52 offset1:1
	ds_read2_b32 v[54:55], v54 offset1:1
	s_waitcnt vmcnt(15) lgkmcnt(8)
	v_pk_fma_f32 v[32:33], v[60:61], v[38:39], v[32:33] op_sel_hi:[1,0,1]
	s_waitcnt lgkmcnt(7)
	v_pk_fma_f32 v[30:31], v[60:61], v[40:41], v[30:31] op_sel_hi:[1,0,1]
	s_waitcnt lgkmcnt(6)
	v_pk_fma_f32 v[28:29], v[60:61], v[42:43], v[28:29] op_sel_hi:[1,0,1]
	s_waitcnt lgkmcnt(5)
	v_pk_fma_f32 v[26:27], v[60:61], v[44:45], v[26:27] op_sel_hi:[1,0,1]
	s_waitcnt lgkmcnt(4)
	v_pk_fma_f32 v[24:25], v[60:61], v[46:47], v[24:25] op_sel_hi:[1,0,1]
	s_waitcnt lgkmcnt(3)
	v_pk_fma_f32 v[22:23], v[60:61], v[48:49], v[22:23] op_sel_hi:[1,0,1]
	s_waitcnt lgkmcnt(2)
	v_pk_fma_f32 v[20:21], v[60:61], v[50:51], v[20:21] op_sel_hi:[1,0,1]
	s_waitcnt lgkmcnt(1)
	v_pk_fma_f32 v[18:19], v[60:61], v[52:53], v[18:19] op_sel_hi:[1,0,1]
	s_waitcnt lgkmcnt(0)
	v_pk_fma_f32 v[16:17], v[60:61], v[54:55], v[16:17] op_sel_hi:[1,0,1]
	global_load_dwordx2 v[60:61], v[94:95], off
	s_waitcnt vmcnt(15)
	v_pk_fma_f32 v[32:33], v[62:63], v[38:39], v[32:33] op_sel:[0,1,0]
	v_pk_fma_f32 v[30:31], v[62:63], v[40:41], v[30:31] op_sel:[0,1,0]
	v_pk_fma_f32 v[28:29], v[62:63], v[42:43], v[28:29] op_sel:[0,1,0]
	v_pk_fma_f32 v[26:27], v[62:63], v[44:45], v[26:27] op_sel:[0,1,0]
	v_pk_fma_f32 v[24:25], v[62:63], v[46:47], v[24:25] op_sel:[0,1,0]
	v_pk_fma_f32 v[22:23], v[62:63], v[48:49], v[22:23] op_sel:[0,1,0]
	v_pk_fma_f32 v[20:21], v[62:63], v[50:51], v[20:21] op_sel:[0,1,0]
	v_pk_fma_f32 v[18:19], v[62:63], v[52:53], v[18:19] op_sel:[0,1,0]
	v_pk_fma_f32 v[16:17], v[62:63], v[54:55], v[16:17] op_sel:[0,1,0]
	s_mov_b32 s0, 0x6000
	v_lshl_add_u64 v[92:93], v[94:95], 0, s[0:1]
	global_load_dwordx2 v[62:63], v[92:93], off
	v_add_u32_e32 v40, 0x1008, v35
	v_add_u32_e32 v42, 0x2008, v35
	v_add_u32_e32 v44, 0x3008, v35
	v_add_u32_e32 v46, 0x4008, v35
	v_add_u32_e32 v48, 0x5008, v35
	v_add_u32_e32 v50, 0x6008, v35
	v_add_u32_e32 v52, 0x7008, v35
	v_add_u32_e32 v54, 0x8008, v35
	ds_read2_b32 v[38:39], v35 offset0:2 offset1:3
	ds_read2_b32 v[40:41], v40 offset1:1
	ds_read2_b32 v[42:43], v42 offset1:1
	ds_read2_b32 v[44:45], v44 offset1:1
	ds_read2_b32 v[46:47], v46 offset1:1
	ds_read2_b32 v[48:49], v48 offset1:1
	ds_read2_b32 v[50:51], v50 offset1:1
	ds_read2_b32 v[52:53], v52 offset1:1
	ds_read2_b32 v[54:55], v54 offset1:1
	s_waitcnt vmcnt(15) lgkmcnt(8)
	v_pk_fma_f32 v[32:33], v[64:65], v[38:39], v[32:33] op_sel_hi:[1,0,1]
	s_waitcnt lgkmcnt(7)
	v_pk_fma_f32 v[30:31], v[64:65], v[40:41], v[30:31] op_sel_hi:[1,0,1]
	s_waitcnt lgkmcnt(6)
	v_pk_fma_f32 v[28:29], v[64:65], v[42:43], v[28:29] op_sel_hi:[1,0,1]
	s_waitcnt lgkmcnt(5)
	v_pk_fma_f32 v[26:27], v[64:65], v[44:45], v[26:27] op_sel_hi:[1,0,1]
	s_waitcnt lgkmcnt(4)
	v_pk_fma_f32 v[24:25], v[64:65], v[46:47], v[24:25] op_sel_hi:[1,0,1]
	s_waitcnt lgkmcnt(3)
	v_pk_fma_f32 v[22:23], v[64:65], v[48:49], v[22:23] op_sel_hi:[1,0,1]
	s_waitcnt lgkmcnt(2)
	v_pk_fma_f32 v[20:21], v[64:65], v[50:51], v[20:21] op_sel_hi:[1,0,1]
	s_waitcnt lgkmcnt(1)
	v_pk_fma_f32 v[18:19], v[64:65], v[52:53], v[18:19] op_sel_hi:[1,0,1]
	s_waitcnt lgkmcnt(0)
	v_pk_fma_f32 v[16:17], v[64:65], v[54:55], v[16:17] op_sel_hi:[1,0,1]
	s_mov_b32 s0, 0xc000
	v_lshl_add_u64 v[92:93], v[94:95], 0, s[0:1]
	global_load_dwordx2 v[64:65], v[92:93], off
	s_waitcnt vmcnt(15)
	v_pk_fma_f32 v[32:33], v[66:67], v[38:39], v[32:33] op_sel:[0,1,0]
	v_pk_fma_f32 v[30:31], v[66:67], v[40:41], v[30:31] op_sel:[0,1,0]
	v_pk_fma_f32 v[28:29], v[66:67], v[42:43], v[28:29] op_sel:[0,1,0]
	v_pk_fma_f32 v[26:27], v[66:67], v[44:45], v[26:27] op_sel:[0,1,0]
	v_pk_fma_f32 v[24:25], v[66:67], v[46:47], v[24:25] op_sel:[0,1,0]
	v_pk_fma_f32 v[22:23], v[66:67], v[48:49], v[22:23] op_sel:[0,1,0]
	v_pk_fma_f32 v[20:21], v[66:67], v[50:51], v[20:21] op_sel:[0,1,0]
	v_pk_fma_f32 v[18:19], v[66:67], v[52:53], v[18:19] op_sel:[0,1,0]
	v_pk_fma_f32 v[16:17], v[66:67], v[54:55], v[16:17] op_sel:[0,1,0]
	s_mov_b32 s0, 0x12000
	v_lshl_add_u64 v[92:93], v[94:95], 0, s[0:1]
	global_load_dwordx2 v[66:67], v[92:93], off
	v_add_u32_e32 v40, 0x1010, v35
	v_add_u32_e32 v42, 0x2010, v35
	v_add_u32_e32 v44, 0x3010, v35
	v_add_u32_e32 v46, 0x4010, v35
	v_add_u32_e32 v48, 0x5010, v35
	v_add_u32_e32 v50, 0x6010, v35
	v_add_u32_e32 v52, 0x7010, v35
	v_add_u32_e32 v54, 0x8010, v35
	ds_read2_b32 v[38:39], v35 offset0:4 offset1:5
	ds_read2_b32 v[40:41], v40 offset1:1
	ds_read2_b32 v[42:43], v42 offset1:1
	ds_read2_b32 v[44:45], v44 offset1:1
	ds_read2_b32 v[46:47], v46 offset1:1
	ds_read2_b32 v[48:49], v48 offset1:1
	ds_read2_b32 v[50:51], v50 offset1:1
	ds_read2_b32 v[52:53], v52 offset1:1
	ds_read2_b32 v[54:55], v54 offset1:1
	s_waitcnt vmcnt(15) lgkmcnt(8)
	v_pk_fma_f32 v[32:33], v[68:69], v[38:39], v[32:33] op_sel_hi:[1,0,1]
	s_waitcnt lgkmcnt(7)
	v_pk_fma_f32 v[30:31], v[68:69], v[40:41], v[30:31] op_sel_hi:[1,0,1]
	s_waitcnt lgkmcnt(6)
	v_pk_fma_f32 v[28:29], v[68:69], v[42:43], v[28:29] op_sel_hi:[1,0,1]
	s_waitcnt lgkmcnt(5)
	v_pk_fma_f32 v[26:27], v[68:69], v[44:45], v[26:27] op_sel_hi:[1,0,1]
	s_waitcnt lgkmcnt(4)
	v_pk_fma_f32 v[24:25], v[68:69], v[46:47], v[24:25] op_sel_hi:[1,0,1]
	s_waitcnt lgkmcnt(3)
	v_pk_fma_f32 v[22:23], v[68:69], v[48:49], v[22:23] op_sel_hi:[1,0,1]
	s_waitcnt lgkmcnt(2)
	v_pk_fma_f32 v[20:21], v[68:69], v[50:51], v[20:21] op_sel_hi:[1,0,1]
	s_waitcnt lgkmcnt(1)
	v_pk_fma_f32 v[18:19], v[68:69], v[52:53], v[18:19] op_sel_hi:[1,0,1]
	s_waitcnt lgkmcnt(0)
	v_pk_fma_f32 v[16:17], v[68:69], v[54:55], v[16:17] op_sel_hi:[1,0,1]
	s_mov_b32 s0, 0x18000
	v_lshl_add_u64 v[92:93], v[94:95], 0, s[0:1]
	global_load_dwordx2 v[68:69], v[92:93], off
	s_waitcnt vmcnt(15)
	v_pk_fma_f32 v[32:33], v[70:71], v[38:39], v[32:33] op_sel:[0,1,0]
	v_pk_fma_f32 v[30:31], v[70:71], v[40:41], v[30:31] op_sel:[0,1,0]
	v_pk_fma_f32 v[28:29], v[70:71], v[42:43], v[28:29] op_sel:[0,1,0]
	v_pk_fma_f32 v[26:27], v[70:71], v[44:45], v[26:27] op_sel:[0,1,0]
	v_pk_fma_f32 v[24:25], v[70:71], v[46:47], v[24:25] op_sel:[0,1,0]
	v_pk_fma_f32 v[22:23], v[70:71], v[48:49], v[22:23] op_sel:[0,1,0]
	v_pk_fma_f32 v[20:21], v[70:71], v[50:51], v[20:21] op_sel:[0,1,0]
	v_pk_fma_f32 v[18:19], v[70:71], v[52:53], v[18:19] op_sel:[0,1,0]
	v_pk_fma_f32 v[16:17], v[70:71], v[54:55], v[16:17] op_sel:[0,1,0]
	s_mov_b32 s0, 0x1e000
	v_lshl_add_u64 v[92:93], v[94:95], 0, s[0:1]
	global_load_dwordx2 v[70:71], v[92:93], off
	v_add_u32_e32 v40, 0x1018, v35
	v_add_u32_e32 v42, 0x2018, v35
	v_add_u32_e32 v44, 0x3018, v35
	v_add_u32_e32 v46, 0x4018, v35
	v_add_u32_e32 v48, 0x5018, v35
	v_add_u32_e32 v50, 0x6018, v35
	v_add_u32_e32 v52, 0x7018, v35
	v_add_u32_e32 v54, 0x8018, v35
	ds_read2_b32 v[38:39], v35 offset0:6 offset1:7
	ds_read2_b32 v[40:41], v40 offset1:1
	ds_read2_b32 v[42:43], v42 offset1:1
	ds_read2_b32 v[44:45], v44 offset1:1
	ds_read2_b32 v[46:47], v46 offset1:1
	ds_read2_b32 v[48:49], v48 offset1:1
	ds_read2_b32 v[50:51], v50 offset1:1
	ds_read2_b32 v[52:53], v52 offset1:1
	ds_read2_b32 v[54:55], v54 offset1:1
	s_waitcnt vmcnt(15) lgkmcnt(8)
	v_pk_fma_f32 v[32:33], v[72:73], v[38:39], v[32:33] op_sel_hi:[1,0,1]
	s_waitcnt lgkmcnt(7)
	v_pk_fma_f32 v[30:31], v[72:73], v[40:41], v[30:31] op_sel_hi:[1,0,1]
	s_waitcnt lgkmcnt(6)
	v_pk_fma_f32 v[28:29], v[72:73], v[42:43], v[28:29] op_sel_hi:[1,0,1]
	s_waitcnt lgkmcnt(5)
	v_pk_fma_f32 v[26:27], v[72:73], v[44:45], v[26:27] op_sel_hi:[1,0,1]
	s_waitcnt lgkmcnt(4)
	v_pk_fma_f32 v[24:25], v[72:73], v[46:47], v[24:25] op_sel_hi:[1,0,1]
	s_waitcnt lgkmcnt(3)
	v_pk_fma_f32 v[22:23], v[72:73], v[48:49], v[22:23] op_sel_hi:[1,0,1]
	s_waitcnt lgkmcnt(2)
	v_pk_fma_f32 v[20:21], v[72:73], v[50:51], v[20:21] op_sel_hi:[1,0,1]
	s_waitcnt lgkmcnt(1)
	v_pk_fma_f32 v[18:19], v[72:73], v[52:53], v[18:19] op_sel_hi:[1,0,1]
	s_waitcnt lgkmcnt(0)
	v_pk_fma_f32 v[16:17], v[72:73], v[54:55], v[16:17] op_sel_hi:[1,0,1]
	s_mov_b32 s0, 0x24000
	v_lshl_add_u64 v[92:93], v[94:95], 0, s[0:1]
	global_load_dwordx2 v[72:73], v[92:93], off
	s_waitcnt vmcnt(15)
	v_pk_fma_f32 v[32:33], v[74:75], v[38:39], v[32:33] op_sel:[0,1,0]
	v_pk_fma_f32 v[30:31], v[74:75], v[40:41], v[30:31] op_sel:[0,1,0]
	v_pk_fma_f32 v[28:29], v[74:75], v[42:43], v[28:29] op_sel:[0,1,0]
	v_pk_fma_f32 v[26:27], v[74:75], v[44:45], v[26:27] op_sel:[0,1,0]
	v_pk_fma_f32 v[24:25], v[74:75], v[46:47], v[24:25] op_sel:[0,1,0]
	v_pk_fma_f32 v[22:23], v[74:75], v[48:49], v[22:23] op_sel:[0,1,0]
	v_pk_fma_f32 v[20:21], v[74:75], v[50:51], v[20:21] op_sel:[0,1,0]
	v_pk_fma_f32 v[18:19], v[74:75], v[52:53], v[18:19] op_sel:[0,1,0]
	v_pk_fma_f32 v[16:17], v[74:75], v[54:55], v[16:17] op_sel:[0,1,0]
	s_mov_b32 s0, 0x2a000
	v_lshl_add_u64 v[92:93], v[94:95], 0, s[0:1]
	global_load_dwordx2 v[74:75], v[92:93], off
	v_add_u32_e32 v40, 0x1020, v35
	v_add_u32_e32 v42, 0x2020, v35
	v_add_u32_e32 v44, 0x3020, v35
	v_add_u32_e32 v46, 0x4020, v35
	v_add_u32_e32 v48, 0x5020, v35
	v_add_u32_e32 v50, 0x6020, v35
	v_add_u32_e32 v52, 0x7020, v35
	v_add_u32_e32 v54, 0x8020, v35
	ds_read2_b32 v[38:39], v35 offset0:8 offset1:9
	ds_read2_b32 v[40:41], v40 offset1:1
	ds_read2_b32 v[42:43], v42 offset1:1
	ds_read2_b32 v[44:45], v44 offset1:1
	ds_read2_b32 v[46:47], v46 offset1:1
	ds_read2_b32 v[48:49], v48 offset1:1
	ds_read2_b32 v[50:51], v50 offset1:1
	ds_read2_b32 v[52:53], v52 offset1:1
	ds_read2_b32 v[54:55], v54 offset1:1
	s_waitcnt vmcnt(15) lgkmcnt(8)
	v_pk_fma_f32 v[32:33], v[76:77], v[38:39], v[32:33] op_sel_hi:[1,0,1]
	s_waitcnt lgkmcnt(7)
	v_pk_fma_f32 v[30:31], v[76:77], v[40:41], v[30:31] op_sel_hi:[1,0,1]
	s_waitcnt lgkmcnt(6)
	v_pk_fma_f32 v[28:29], v[76:77], v[42:43], v[28:29] op_sel_hi:[1,0,1]
	s_waitcnt lgkmcnt(5)
	v_pk_fma_f32 v[26:27], v[76:77], v[44:45], v[26:27] op_sel_hi:[1,0,1]
	s_waitcnt lgkmcnt(4)
	v_pk_fma_f32 v[24:25], v[76:77], v[46:47], v[24:25] op_sel_hi:[1,0,1]
	s_waitcnt lgkmcnt(3)
	v_pk_fma_f32 v[22:23], v[76:77], v[48:49], v[22:23] op_sel_hi:[1,0,1]
	s_waitcnt lgkmcnt(2)
	v_pk_fma_f32 v[20:21], v[76:77], v[50:51], v[20:21] op_sel_hi:[1,0,1]
	s_waitcnt lgkmcnt(1)
	v_pk_fma_f32 v[18:19], v[76:77], v[52:53], v[18:19] op_sel_hi:[1,0,1]
	s_waitcnt lgkmcnt(0)
	v_pk_fma_f32 v[16:17], v[76:77], v[54:55], v[16:17] op_sel_hi:[1,0,1]
	s_mov_b32 s0, 0x30000
	v_lshl_add_u64 v[92:93], v[94:95], 0, s[0:1]
	global_load_dwordx2 v[76:77], v[92:93], off
	s_waitcnt vmcnt(15)
	v_pk_fma_f32 v[32:33], v[78:79], v[38:39], v[32:33] op_sel:[0,1,0]
	v_pk_fma_f32 v[30:31], v[78:79], v[40:41], v[30:31] op_sel:[0,1,0]
	v_pk_fma_f32 v[28:29], v[78:79], v[42:43], v[28:29] op_sel:[0,1,0]
	v_pk_fma_f32 v[26:27], v[78:79], v[44:45], v[26:27] op_sel:[0,1,0]
	v_pk_fma_f32 v[24:25], v[78:79], v[46:47], v[24:25] op_sel:[0,1,0]
	v_pk_fma_f32 v[22:23], v[78:79], v[48:49], v[22:23] op_sel:[0,1,0]
	v_pk_fma_f32 v[20:21], v[78:79], v[50:51], v[20:21] op_sel:[0,1,0]
	v_pk_fma_f32 v[18:19], v[78:79], v[52:53], v[18:19] op_sel:[0,1,0]
	v_pk_fma_f32 v[16:17], v[78:79], v[54:55], v[16:17] op_sel:[0,1,0]
	s_mov_b32 s0, 0x36000
	v_lshl_add_u64 v[92:93], v[94:95], 0, s[0:1]
	global_load_dwordx2 v[78:79], v[92:93], off
	v_add_u32_e32 v40, 0x1028, v35
	v_add_u32_e32 v42, 0x2028, v35
	v_add_u32_e32 v44, 0x3028, v35
	v_add_u32_e32 v46, 0x4028, v35
	v_add_u32_e32 v48, 0x5028, v35
	v_add_u32_e32 v50, 0x6028, v35
	v_add_u32_e32 v52, 0x7028, v35
	v_add_u32_e32 v54, 0x8028, v35
	ds_read2_b32 v[38:39], v35 offset0:10 offset1:11
	ds_read2_b32 v[40:41], v40 offset1:1
	ds_read2_b32 v[42:43], v42 offset1:1
	ds_read2_b32 v[44:45], v44 offset1:1
	ds_read2_b32 v[46:47], v46 offset1:1
	ds_read2_b32 v[48:49], v48 offset1:1
	ds_read2_b32 v[50:51], v50 offset1:1
	ds_read2_b32 v[52:53], v52 offset1:1
	ds_read2_b32 v[54:55], v54 offset1:1
	s_waitcnt vmcnt(15) lgkmcnt(8)
	v_pk_fma_f32 v[32:33], v[80:81], v[38:39], v[32:33] op_sel_hi:[1,0,1]
	s_waitcnt lgkmcnt(7)
	v_pk_fma_f32 v[30:31], v[80:81], v[40:41], v[30:31] op_sel_hi:[1,0,1]
	s_waitcnt lgkmcnt(6)
	v_pk_fma_f32 v[28:29], v[80:81], v[42:43], v[28:29] op_sel_hi:[1,0,1]
	s_waitcnt lgkmcnt(5)
	v_pk_fma_f32 v[26:27], v[80:81], v[44:45], v[26:27] op_sel_hi:[1,0,1]
	s_waitcnt lgkmcnt(4)
	v_pk_fma_f32 v[24:25], v[80:81], v[46:47], v[24:25] op_sel_hi:[1,0,1]
	s_waitcnt lgkmcnt(3)
	v_pk_fma_f32 v[22:23], v[80:81], v[48:49], v[22:23] op_sel_hi:[1,0,1]
	s_waitcnt lgkmcnt(2)
	v_pk_fma_f32 v[20:21], v[80:81], v[50:51], v[20:21] op_sel_hi:[1,0,1]
	s_waitcnt lgkmcnt(1)
	v_pk_fma_f32 v[18:19], v[80:81], v[52:53], v[18:19] op_sel_hi:[1,0,1]
	s_waitcnt lgkmcnt(0)
	v_pk_fma_f32 v[16:17], v[80:81], v[54:55], v[16:17] op_sel_hi:[1,0,1]
	s_mov_b32 s0, 0x3c000
	v_lshl_add_u64 v[92:93], v[94:95], 0, s[0:1]
	global_load_dwordx2 v[80:81], v[92:93], off
	s_waitcnt vmcnt(15)
	v_pk_fma_f32 v[32:33], v[82:83], v[38:39], v[32:33] op_sel:[0,1,0]
	v_pk_fma_f32 v[30:31], v[82:83], v[40:41], v[30:31] op_sel:[0,1,0]
	v_pk_fma_f32 v[28:29], v[82:83], v[42:43], v[28:29] op_sel:[0,1,0]
	v_pk_fma_f32 v[26:27], v[82:83], v[44:45], v[26:27] op_sel:[0,1,0]
	v_pk_fma_f32 v[24:25], v[82:83], v[46:47], v[24:25] op_sel:[0,1,0]
	v_pk_fma_f32 v[22:23], v[82:83], v[48:49], v[22:23] op_sel:[0,1,0]
	v_pk_fma_f32 v[20:21], v[82:83], v[50:51], v[20:21] op_sel:[0,1,0]
	v_pk_fma_f32 v[18:19], v[82:83], v[52:53], v[18:19] op_sel:[0,1,0]
	v_pk_fma_f32 v[16:17], v[82:83], v[54:55], v[16:17] op_sel:[0,1,0]
	s_mov_b32 s0, 0x42000
	v_lshl_add_u64 v[92:93], v[94:95], 0, s[0:1]
	global_load_dwordx2 v[82:83], v[92:93], off
	v_add_u32_e32 v40, 0x1030, v35
	v_add_u32_e32 v42, 0x2030, v35
	v_add_u32_e32 v44, 0x3030, v35
	v_add_u32_e32 v46, 0x4030, v35
	v_add_u32_e32 v48, 0x5030, v35
	v_add_u32_e32 v50, 0x6030, v35
	v_add_u32_e32 v52, 0x7030, v35
	v_add_u32_e32 v54, 0x8030, v35
	ds_read2_b32 v[38:39], v35 offset0:12 offset1:13
	ds_read2_b32 v[40:41], v40 offset1:1
	ds_read2_b32 v[42:43], v42 offset1:1
	ds_read2_b32 v[44:45], v44 offset1:1
	ds_read2_b32 v[46:47], v46 offset1:1
	ds_read2_b32 v[48:49], v48 offset1:1
	ds_read2_b32 v[50:51], v50 offset1:1
	ds_read2_b32 v[52:53], v52 offset1:1
	ds_read2_b32 v[54:55], v54 offset1:1
	s_waitcnt vmcnt(15) lgkmcnt(8)
	v_pk_fma_f32 v[32:33], v[84:85], v[38:39], v[32:33] op_sel_hi:[1,0,1]
	s_waitcnt lgkmcnt(7)
	v_pk_fma_f32 v[30:31], v[84:85], v[40:41], v[30:31] op_sel_hi:[1,0,1]
	s_waitcnt lgkmcnt(6)
	v_pk_fma_f32 v[28:29], v[84:85], v[42:43], v[28:29] op_sel_hi:[1,0,1]
	s_waitcnt lgkmcnt(5)
	v_pk_fma_f32 v[26:27], v[84:85], v[44:45], v[26:27] op_sel_hi:[1,0,1]
	s_waitcnt lgkmcnt(4)
	v_pk_fma_f32 v[24:25], v[84:85], v[46:47], v[24:25] op_sel_hi:[1,0,1]
	s_waitcnt lgkmcnt(3)
	v_pk_fma_f32 v[22:23], v[84:85], v[48:49], v[22:23] op_sel_hi:[1,0,1]
	s_waitcnt lgkmcnt(2)
	v_pk_fma_f32 v[20:21], v[84:85], v[50:51], v[20:21] op_sel_hi:[1,0,1]
	s_waitcnt lgkmcnt(1)
	v_pk_fma_f32 v[18:19], v[84:85], v[52:53], v[18:19] op_sel_hi:[1,0,1]
	s_waitcnt lgkmcnt(0)
	v_pk_fma_f32 v[16:17], v[84:85], v[54:55], v[16:17] op_sel_hi:[1,0,1]
	s_mov_b32 s0, 0x48000
	v_lshl_add_u64 v[92:93], v[94:95], 0, s[0:1]
	global_load_dwordx2 v[84:85], v[92:93], off
	s_waitcnt vmcnt(15)
	v_pk_fma_f32 v[32:33], v[86:87], v[38:39], v[32:33] op_sel:[0,1,0]
	v_pk_fma_f32 v[30:31], v[86:87], v[40:41], v[30:31] op_sel:[0,1,0]
	v_pk_fma_f32 v[28:29], v[86:87], v[42:43], v[28:29] op_sel:[0,1,0]
	v_pk_fma_f32 v[26:27], v[86:87], v[44:45], v[26:27] op_sel:[0,1,0]
	v_pk_fma_f32 v[24:25], v[86:87], v[46:47], v[24:25] op_sel:[0,1,0]
	v_pk_fma_f32 v[22:23], v[86:87], v[48:49], v[22:23] op_sel:[0,1,0]
	v_pk_fma_f32 v[20:21], v[86:87], v[50:51], v[20:21] op_sel:[0,1,0]
	v_pk_fma_f32 v[18:19], v[86:87], v[52:53], v[18:19] op_sel:[0,1,0]
	v_pk_fma_f32 v[16:17], v[86:87], v[54:55], v[16:17] op_sel:[0,1,0]
	s_mov_b32 s0, 0x4e000
	v_lshl_add_u64 v[92:93], v[94:95], 0, s[0:1]
	global_load_dwordx2 v[86:87], v[92:93], off
	v_add_u32_e32 v40, 0x1038, v35
	v_add_u32_e32 v42, 0x2038, v35
	v_add_u32_e32 v44, 0x3038, v35
	v_add_u32_e32 v46, 0x4038, v35
	v_add_u32_e32 v48, 0x5038, v35
	v_add_u32_e32 v50, 0x6038, v35
	v_add_u32_e32 v52, 0x7038, v35
	v_add_u32_e32 v54, 0x8038, v35
	ds_read2_b32 v[38:39], v35 offset0:14 offset1:15
	ds_read2_b32 v[40:41], v40 offset1:1
	ds_read2_b32 v[42:43], v42 offset1:1
	ds_read2_b32 v[44:45], v44 offset1:1
	ds_read2_b32 v[46:47], v46 offset1:1
	ds_read2_b32 v[48:49], v48 offset1:1
	ds_read2_b32 v[50:51], v50 offset1:1
	ds_read2_b32 v[52:53], v52 offset1:1
	ds_read2_b32 v[54:55], v54 offset1:1
	v_add_u32_e32 v35, 64, v35
	s_waitcnt vmcnt(15) lgkmcnt(8)
	v_pk_fma_f32 v[32:33], v[88:89], v[38:39], v[32:33] op_sel_hi:[1,0,1]
	s_waitcnt lgkmcnt(7)
	v_pk_fma_f32 v[30:31], v[88:89], v[40:41], v[30:31] op_sel_hi:[1,0,1]
	s_waitcnt lgkmcnt(6)
	v_pk_fma_f32 v[28:29], v[88:89], v[42:43], v[28:29] op_sel_hi:[1,0,1]
	s_waitcnt lgkmcnt(5)
	v_pk_fma_f32 v[26:27], v[88:89], v[44:45], v[26:27] op_sel_hi:[1,0,1]
	s_waitcnt lgkmcnt(4)
	v_pk_fma_f32 v[24:25], v[88:89], v[46:47], v[24:25] op_sel_hi:[1,0,1]
	s_waitcnt lgkmcnt(3)
	v_pk_fma_f32 v[22:23], v[88:89], v[48:49], v[22:23] op_sel_hi:[1,0,1]
	s_waitcnt lgkmcnt(2)
	v_pk_fma_f32 v[20:21], v[88:89], v[50:51], v[20:21] op_sel_hi:[1,0,1]
	s_waitcnt lgkmcnt(1)
	v_pk_fma_f32 v[18:19], v[88:89], v[52:53], v[18:19] op_sel_hi:[1,0,1]
	s_waitcnt lgkmcnt(0)
	v_pk_fma_f32 v[16:17], v[88:89], v[54:55], v[16:17] op_sel_hi:[1,0,1]
	s_mov_b32 s0, 0x54000
	v_lshl_add_u64 v[92:93], v[94:95], 0, s[0:1]
	global_load_dwordx2 v[88:89], v[92:93], off
	s_waitcnt vmcnt(15)
	v_pk_fma_f32 v[32:33], v[90:91], v[38:39], v[32:33] op_sel:[0,1,0]
	v_pk_fma_f32 v[30:31], v[90:91], v[40:41], v[30:31] op_sel:[0,1,0]
	v_pk_fma_f32 v[28:29], v[90:91], v[42:43], v[28:29] op_sel:[0,1,0]
	v_pk_fma_f32 v[26:27], v[90:91], v[44:45], v[26:27] op_sel:[0,1,0]
	v_pk_fma_f32 v[24:25], v[90:91], v[46:47], v[24:25] op_sel:[0,1,0]
	v_pk_fma_f32 v[22:23], v[90:91], v[48:49], v[22:23] op_sel:[0,1,0]
	v_pk_fma_f32 v[20:21], v[90:91], v[50:51], v[20:21] op_sel:[0,1,0]
	v_pk_fma_f32 v[18:19], v[90:91], v[52:53], v[18:19] op_sel:[0,1,0]
	v_pk_fma_f32 v[16:17], v[90:91], v[54:55], v[16:17] op_sel:[0,1,0]
	s_mov_b32 s0, 0x5a000
	v_lshl_add_u64 v[92:93], v[94:95], 0, s[0:1]
	global_load_dwordx2 v[90:91], v[92:93], off
	s_mov_b64 s[6:7], s[40:41]
	s_cmp_eq_u32 s6, 0x2a0000
	s_cbranch_scc0 .LBB0_50
	v_add_u32_e32 v40, 0x1000, v35
	v_add_u32_e32 v42, 0x2000, v35
	v_add_u32_e32 v44, 0x3000, v35
	v_add_u32_e32 v46, 0x4000, v35
	v_add_u32_e32 v48, 0x5000, v35
	v_add_u32_e32 v50, 0x6000, v35
	v_add_u32_e32 v52, 0x7000, v35
	v_add_u32_e32 v54, 0x8000, v35
	ds_read2_b32 v[38:39], v35 offset1:1
	ds_read2_b32 v[40:41], v40 offset1:1
	ds_read2_b32 v[42:43], v42 offset1:1
	ds_read2_b32 v[44:45], v44 offset1:1
	ds_read2_b32 v[46:47], v46 offset1:1
	ds_read2_b32 v[48:49], v48 offset1:1
	ds_read2_b32 v[50:51], v50 offset1:1
	ds_read2_b32 v[52:53], v52 offset1:1
	ds_read2_b32 v[54:55], v54 offset1:1
	s_waitcnt vmcnt(15) lgkmcnt(8)
	v_pk_fma_f32 v[32:33], v[60:61], v[38:39], v[32:33] op_sel_hi:[1,0,1]
	s_waitcnt lgkmcnt(7)
	v_pk_fma_f32 v[30:31], v[60:61], v[40:41], v[30:31] op_sel_hi:[1,0,1]
	s_waitcnt lgkmcnt(6)
	v_pk_fma_f32 v[28:29], v[60:61], v[42:43], v[28:29] op_sel_hi:[1,0,1]
	s_waitcnt lgkmcnt(5)
	v_pk_fma_f32 v[26:27], v[60:61], v[44:45], v[26:27] op_sel_hi:[1,0,1]
	s_waitcnt lgkmcnt(4)
	v_pk_fma_f32 v[24:25], v[60:61], v[46:47], v[24:25] op_sel_hi:[1,0,1]
	s_waitcnt lgkmcnt(3)
	v_pk_fma_f32 v[22:23], v[60:61], v[48:49], v[22:23] op_sel_hi:[1,0,1]
	s_waitcnt lgkmcnt(2)
	v_pk_fma_f32 v[20:21], v[60:61], v[50:51], v[20:21] op_sel_hi:[1,0,1]
	s_waitcnt lgkmcnt(1)
	v_pk_fma_f32 v[18:19], v[60:61], v[52:53], v[18:19] op_sel_hi:[1,0,1]
	s_waitcnt lgkmcnt(0)
	v_pk_fma_f32 v[16:17], v[60:61], v[54:55], v[16:17] op_sel_hi:[1,0,1]
	s_waitcnt vmcnt(14)
	v_pk_fma_f32 v[32:33], v[62:63], v[38:39], v[32:33] op_sel:[0,1,0]
	v_pk_fma_f32 v[30:31], v[62:63], v[40:41], v[30:31] op_sel:[0,1,0]
	v_pk_fma_f32 v[28:29], v[62:63], v[42:43], v[28:29] op_sel:[0,1,0]
	v_pk_fma_f32 v[26:27], v[62:63], v[44:45], v[26:27] op_sel:[0,1,0]
	v_pk_fma_f32 v[24:25], v[62:63], v[46:47], v[24:25] op_sel:[0,1,0]
	v_pk_fma_f32 v[22:23], v[62:63], v[48:49], v[22:23] op_sel:[0,1,0]
	v_pk_fma_f32 v[20:21], v[62:63], v[50:51], v[20:21] op_sel:[0,1,0]
	v_pk_fma_f32 v[18:19], v[62:63], v[52:53], v[18:19] op_sel:[0,1,0]
	v_pk_fma_f32 v[16:17], v[62:63], v[54:55], v[16:17] op_sel:[0,1,0]
	v_add_u32_e32 v40, 0x1008, v35
	v_add_u32_e32 v42, 0x2008, v35
	v_add_u32_e32 v44, 0x3008, v35
	v_add_u32_e32 v46, 0x4008, v35
	v_add_u32_e32 v48, 0x5008, v35
	v_add_u32_e32 v50, 0x6008, v35
	v_add_u32_e32 v52, 0x7008, v35
	v_add_u32_e32 v54, 0x8008, v35
	ds_read2_b32 v[38:39], v35 offset0:2 offset1:3
	ds_read2_b32 v[40:41], v40 offset1:1
	ds_read2_b32 v[42:43], v42 offset1:1
	ds_read2_b32 v[44:45], v44 offset1:1
	ds_read2_b32 v[46:47], v46 offset1:1
	ds_read2_b32 v[48:49], v48 offset1:1
	ds_read2_b32 v[50:51], v50 offset1:1
	ds_read2_b32 v[52:53], v52 offset1:1
	ds_read2_b32 v[54:55], v54 offset1:1
	s_waitcnt vmcnt(13) lgkmcnt(8)
	v_pk_fma_f32 v[32:33], v[64:65], v[38:39], v[32:33] op_sel_hi:[1,0,1]
	s_waitcnt lgkmcnt(7)
	v_pk_fma_f32 v[30:31], v[64:65], v[40:41], v[30:31] op_sel_hi:[1,0,1]
	s_waitcnt lgkmcnt(6)
	v_pk_fma_f32 v[28:29], v[64:65], v[42:43], v[28:29] op_sel_hi:[1,0,1]
	s_waitcnt lgkmcnt(5)
	v_pk_fma_f32 v[26:27], v[64:65], v[44:45], v[26:27] op_sel_hi:[1,0,1]
	s_waitcnt lgkmcnt(4)
	v_pk_fma_f32 v[24:25], v[64:65], v[46:47], v[24:25] op_sel_hi:[1,0,1]
	s_waitcnt lgkmcnt(3)
	v_pk_fma_f32 v[22:23], v[64:65], v[48:49], v[22:23] op_sel_hi:[1,0,1]
	s_waitcnt lgkmcnt(2)
	v_pk_fma_f32 v[20:21], v[64:65], v[50:51], v[20:21] op_sel_hi:[1,0,1]
	s_waitcnt lgkmcnt(1)
	v_pk_fma_f32 v[18:19], v[64:65], v[52:53], v[18:19] op_sel_hi:[1,0,1]
	s_waitcnt lgkmcnt(0)
	v_pk_fma_f32 v[16:17], v[64:65], v[54:55], v[16:17] op_sel_hi:[1,0,1]
	s_waitcnt vmcnt(12)
	v_pk_fma_f32 v[32:33], v[66:67], v[38:39], v[32:33] op_sel:[0,1,0]
	v_pk_fma_f32 v[30:31], v[66:67], v[40:41], v[30:31] op_sel:[0,1,0]
	v_pk_fma_f32 v[28:29], v[66:67], v[42:43], v[28:29] op_sel:[0,1,0]
	v_pk_fma_f32 v[26:27], v[66:67], v[44:45], v[26:27] op_sel:[0,1,0]
	v_pk_fma_f32 v[24:25], v[66:67], v[46:47], v[24:25] op_sel:[0,1,0]
	v_pk_fma_f32 v[22:23], v[66:67], v[48:49], v[22:23] op_sel:[0,1,0]
	v_pk_fma_f32 v[20:21], v[66:67], v[50:51], v[20:21] op_sel:[0,1,0]
	v_pk_fma_f32 v[18:19], v[66:67], v[52:53], v[18:19] op_sel:[0,1,0]
	v_pk_fma_f32 v[16:17], v[66:67], v[54:55], v[16:17] op_sel:[0,1,0]
	v_add_u32_e32 v40, 0x1010, v35
	v_add_u32_e32 v42, 0x2010, v35
	v_add_u32_e32 v44, 0x3010, v35
	v_add_u32_e32 v46, 0x4010, v35
	v_add_u32_e32 v48, 0x5010, v35
	v_add_u32_e32 v50, 0x6010, v35
	v_add_u32_e32 v52, 0x7010, v35
	v_add_u32_e32 v54, 0x8010, v35
	ds_read2_b32 v[38:39], v35 offset0:4 offset1:5
	ds_read2_b32 v[40:41], v40 offset1:1
	ds_read2_b32 v[42:43], v42 offset1:1
	ds_read2_b32 v[44:45], v44 offset1:1
	ds_read2_b32 v[46:47], v46 offset1:1
	ds_read2_b32 v[48:49], v48 offset1:1
	ds_read2_b32 v[50:51], v50 offset1:1
	ds_read2_b32 v[52:53], v52 offset1:1
	ds_read2_b32 v[54:55], v54 offset1:1
	s_waitcnt vmcnt(11) lgkmcnt(8)
	v_pk_fma_f32 v[32:33], v[68:69], v[38:39], v[32:33] op_sel_hi:[1,0,1]
	s_waitcnt lgkmcnt(7)
	v_pk_fma_f32 v[30:31], v[68:69], v[40:41], v[30:31] op_sel_hi:[1,0,1]
	s_waitcnt lgkmcnt(6)
	v_pk_fma_f32 v[28:29], v[68:69], v[42:43], v[28:29] op_sel_hi:[1,0,1]
	s_waitcnt lgkmcnt(5)
	v_pk_fma_f32 v[26:27], v[68:69], v[44:45], v[26:27] op_sel_hi:[1,0,1]
	s_waitcnt lgkmcnt(4)
	v_pk_fma_f32 v[24:25], v[68:69], v[46:47], v[24:25] op_sel_hi:[1,0,1]
	s_waitcnt lgkmcnt(3)
	v_pk_fma_f32 v[22:23], v[68:69], v[48:49], v[22:23] op_sel_hi:[1,0,1]
	s_waitcnt lgkmcnt(2)
	v_pk_fma_f32 v[20:21], v[68:69], v[50:51], v[20:21] op_sel_hi:[1,0,1]
	s_waitcnt lgkmcnt(1)
	v_pk_fma_f32 v[18:19], v[68:69], v[52:53], v[18:19] op_sel_hi:[1,0,1]
	s_waitcnt lgkmcnt(0)
	v_pk_fma_f32 v[16:17], v[68:69], v[54:55], v[16:17] op_sel_hi:[1,0,1]
	s_waitcnt vmcnt(10)
	v_pk_fma_f32 v[32:33], v[70:71], v[38:39], v[32:33] op_sel:[0,1,0]
	v_pk_fma_f32 v[30:31], v[70:71], v[40:41], v[30:31] op_sel:[0,1,0]
	v_pk_fma_f32 v[28:29], v[70:71], v[42:43], v[28:29] op_sel:[0,1,0]
	v_pk_fma_f32 v[26:27], v[70:71], v[44:45], v[26:27] op_sel:[0,1,0]
	v_pk_fma_f32 v[24:25], v[70:71], v[46:47], v[24:25] op_sel:[0,1,0]
	v_pk_fma_f32 v[22:23], v[70:71], v[48:49], v[22:23] op_sel:[0,1,0]
	v_pk_fma_f32 v[20:21], v[70:71], v[50:51], v[20:21] op_sel:[0,1,0]
	v_pk_fma_f32 v[18:19], v[70:71], v[52:53], v[18:19] op_sel:[0,1,0]
	v_pk_fma_f32 v[16:17], v[70:71], v[54:55], v[16:17] op_sel:[0,1,0]
	v_add_u32_e32 v40, 0x1018, v35
	v_add_u32_e32 v42, 0x2018, v35
	v_add_u32_e32 v44, 0x3018, v35
	v_add_u32_e32 v46, 0x4018, v35
	v_add_u32_e32 v48, 0x5018, v35
	v_add_u32_e32 v50, 0x6018, v35
	v_add_u32_e32 v52, 0x7018, v35
	v_add_u32_e32 v54, 0x8018, v35
	ds_read2_b32 v[38:39], v35 offset0:6 offset1:7
	ds_read2_b32 v[40:41], v40 offset1:1
	ds_read2_b32 v[42:43], v42 offset1:1
	ds_read2_b32 v[44:45], v44 offset1:1
	ds_read2_b32 v[46:47], v46 offset1:1
	ds_read2_b32 v[48:49], v48 offset1:1
	ds_read2_b32 v[50:51], v50 offset1:1
	ds_read2_b32 v[52:53], v52 offset1:1
	ds_read2_b32 v[54:55], v54 offset1:1
	s_waitcnt vmcnt(9) lgkmcnt(8)
	v_pk_fma_f32 v[32:33], v[72:73], v[38:39], v[32:33] op_sel_hi:[1,0,1]
	s_waitcnt lgkmcnt(7)
	v_pk_fma_f32 v[30:31], v[72:73], v[40:41], v[30:31] op_sel_hi:[1,0,1]
	s_waitcnt lgkmcnt(6)
	v_pk_fma_f32 v[28:29], v[72:73], v[42:43], v[28:29] op_sel_hi:[1,0,1]
	s_waitcnt lgkmcnt(5)
	v_pk_fma_f32 v[26:27], v[72:73], v[44:45], v[26:27] op_sel_hi:[1,0,1]
	s_waitcnt lgkmcnt(4)
	v_pk_fma_f32 v[24:25], v[72:73], v[46:47], v[24:25] op_sel_hi:[1,0,1]
	s_waitcnt lgkmcnt(3)
	v_pk_fma_f32 v[22:23], v[72:73], v[48:49], v[22:23] op_sel_hi:[1,0,1]
	s_waitcnt lgkmcnt(2)
	v_pk_fma_f32 v[20:21], v[72:73], v[50:51], v[20:21] op_sel_hi:[1,0,1]
	s_waitcnt lgkmcnt(1)
	v_pk_fma_f32 v[18:19], v[72:73], v[52:53], v[18:19] op_sel_hi:[1,0,1]
	s_waitcnt lgkmcnt(0)
	v_pk_fma_f32 v[16:17], v[72:73], v[54:55], v[16:17] op_sel_hi:[1,0,1]
	s_waitcnt vmcnt(8)
	v_pk_fma_f32 v[32:33], v[74:75], v[38:39], v[32:33] op_sel:[0,1,0]
	v_pk_fma_f32 v[30:31], v[74:75], v[40:41], v[30:31] op_sel:[0,1,0]
	v_pk_fma_f32 v[28:29], v[74:75], v[42:43], v[28:29] op_sel:[0,1,0]
	v_pk_fma_f32 v[26:27], v[74:75], v[44:45], v[26:27] op_sel:[0,1,0]
	v_pk_fma_f32 v[24:25], v[74:75], v[46:47], v[24:25] op_sel:[0,1,0]
	v_pk_fma_f32 v[22:23], v[74:75], v[48:49], v[22:23] op_sel:[0,1,0]
	v_pk_fma_f32 v[20:21], v[74:75], v[50:51], v[20:21] op_sel:[0,1,0]
	v_pk_fma_f32 v[18:19], v[74:75], v[52:53], v[18:19] op_sel:[0,1,0]
	v_pk_fma_f32 v[16:17], v[74:75], v[54:55], v[16:17] op_sel:[0,1,0]
	v_add_u32_e32 v40, 0x1020, v35
	v_add_u32_e32 v42, 0x2020, v35
	v_add_u32_e32 v44, 0x3020, v35
	v_add_u32_e32 v46, 0x4020, v35
	v_add_u32_e32 v48, 0x5020, v35
	v_add_u32_e32 v50, 0x6020, v35
	v_add_u32_e32 v52, 0x7020, v35
	v_add_u32_e32 v54, 0x8020, v35
	ds_read2_b32 v[38:39], v35 offset0:8 offset1:9
	ds_read2_b32 v[40:41], v40 offset1:1
	ds_read2_b32 v[42:43], v42 offset1:1
	ds_read2_b32 v[44:45], v44 offset1:1
	ds_read2_b32 v[46:47], v46 offset1:1
	ds_read2_b32 v[48:49], v48 offset1:1
	ds_read2_b32 v[50:51], v50 offset1:1
	ds_read2_b32 v[52:53], v52 offset1:1
	ds_read2_b32 v[54:55], v54 offset1:1
	s_waitcnt vmcnt(7) lgkmcnt(8)
	v_pk_fma_f32 v[32:33], v[76:77], v[38:39], v[32:33] op_sel_hi:[1,0,1]
	s_waitcnt lgkmcnt(7)
	v_pk_fma_f32 v[30:31], v[76:77], v[40:41], v[30:31] op_sel_hi:[1,0,1]
	s_waitcnt lgkmcnt(6)
	v_pk_fma_f32 v[28:29], v[76:77], v[42:43], v[28:29] op_sel_hi:[1,0,1]
	s_waitcnt lgkmcnt(5)
	v_pk_fma_f32 v[26:27], v[76:77], v[44:45], v[26:27] op_sel_hi:[1,0,1]
	s_waitcnt lgkmcnt(4)
	v_pk_fma_f32 v[24:25], v[76:77], v[46:47], v[24:25] op_sel_hi:[1,0,1]
	s_waitcnt lgkmcnt(3)
	v_pk_fma_f32 v[22:23], v[76:77], v[48:49], v[22:23] op_sel_hi:[1,0,1]
	s_waitcnt lgkmcnt(2)
	v_pk_fma_f32 v[20:21], v[76:77], v[50:51], v[20:21] op_sel_hi:[1,0,1]
	s_waitcnt lgkmcnt(1)
	v_pk_fma_f32 v[18:19], v[76:77], v[52:53], v[18:19] op_sel_hi:[1,0,1]
	s_waitcnt lgkmcnt(0)
	v_pk_fma_f32 v[16:17], v[76:77], v[54:55], v[16:17] op_sel_hi:[1,0,1]
	s_waitcnt vmcnt(6)
	v_pk_fma_f32 v[32:33], v[78:79], v[38:39], v[32:33] op_sel:[0,1,0]
	v_pk_fma_f32 v[30:31], v[78:79], v[40:41], v[30:31] op_sel:[0,1,0]
	v_pk_fma_f32 v[28:29], v[78:79], v[42:43], v[28:29] op_sel:[0,1,0]
	v_pk_fma_f32 v[26:27], v[78:79], v[44:45], v[26:27] op_sel:[0,1,0]
	v_pk_fma_f32 v[24:25], v[78:79], v[46:47], v[24:25] op_sel:[0,1,0]
	v_pk_fma_f32 v[22:23], v[78:79], v[48:49], v[22:23] op_sel:[0,1,0]
	v_pk_fma_f32 v[20:21], v[78:79], v[50:51], v[20:21] op_sel:[0,1,0]
	v_pk_fma_f32 v[18:19], v[78:79], v[52:53], v[18:19] op_sel:[0,1,0]
	v_pk_fma_f32 v[16:17], v[78:79], v[54:55], v[16:17] op_sel:[0,1,0]
	v_add_u32_e32 v40, 0x1028, v35
	v_add_u32_e32 v42, 0x2028, v35
	v_add_u32_e32 v44, 0x3028, v35
	v_add_u32_e32 v46, 0x4028, v35
	v_add_u32_e32 v48, 0x5028, v35
	v_add_u32_e32 v50, 0x6028, v35
	v_add_u32_e32 v52, 0x7028, v35
	v_add_u32_e32 v54, 0x8028, v35
	ds_read2_b32 v[38:39], v35 offset0:10 offset1:11
	ds_read2_b32 v[40:41], v40 offset1:1
	ds_read2_b32 v[42:43], v42 offset1:1
	ds_read2_b32 v[44:45], v44 offset1:1
	ds_read2_b32 v[46:47], v46 offset1:1
	ds_read2_b32 v[48:49], v48 offset1:1
	ds_read2_b32 v[50:51], v50 offset1:1
	ds_read2_b32 v[52:53], v52 offset1:1
	ds_read2_b32 v[54:55], v54 offset1:1
	s_waitcnt vmcnt(5) lgkmcnt(8)
	v_pk_fma_f32 v[32:33], v[80:81], v[38:39], v[32:33] op_sel_hi:[1,0,1]
	s_waitcnt lgkmcnt(7)
	v_pk_fma_f32 v[30:31], v[80:81], v[40:41], v[30:31] op_sel_hi:[1,0,1]
	s_waitcnt lgkmcnt(6)
	v_pk_fma_f32 v[28:29], v[80:81], v[42:43], v[28:29] op_sel_hi:[1,0,1]
	s_waitcnt lgkmcnt(5)
	v_pk_fma_f32 v[26:27], v[80:81], v[44:45], v[26:27] op_sel_hi:[1,0,1]
	s_waitcnt lgkmcnt(4)
	v_pk_fma_f32 v[24:25], v[80:81], v[46:47], v[24:25] op_sel_hi:[1,0,1]
	s_waitcnt lgkmcnt(3)
	v_pk_fma_f32 v[22:23], v[80:81], v[48:49], v[22:23] op_sel_hi:[1,0,1]
	s_waitcnt lgkmcnt(2)
	v_pk_fma_f32 v[20:21], v[80:81], v[50:51], v[20:21] op_sel_hi:[1,0,1]
	s_waitcnt lgkmcnt(1)
	v_pk_fma_f32 v[18:19], v[80:81], v[52:53], v[18:19] op_sel_hi:[1,0,1]
	s_waitcnt lgkmcnt(0)
	v_pk_fma_f32 v[16:17], v[80:81], v[54:55], v[16:17] op_sel_hi:[1,0,1]
	s_waitcnt vmcnt(4)
	v_pk_fma_f32 v[32:33], v[82:83], v[38:39], v[32:33] op_sel:[0,1,0]
	v_pk_fma_f32 v[30:31], v[82:83], v[40:41], v[30:31] op_sel:[0,1,0]
	v_pk_fma_f32 v[28:29], v[82:83], v[42:43], v[28:29] op_sel:[0,1,0]
	v_pk_fma_f32 v[26:27], v[82:83], v[44:45], v[26:27] op_sel:[0,1,0]
	v_pk_fma_f32 v[24:25], v[82:83], v[46:47], v[24:25] op_sel:[0,1,0]
	v_pk_fma_f32 v[22:23], v[82:83], v[48:49], v[22:23] op_sel:[0,1,0]
	v_pk_fma_f32 v[20:21], v[82:83], v[50:51], v[20:21] op_sel:[0,1,0]
	v_pk_fma_f32 v[18:19], v[82:83], v[52:53], v[18:19] op_sel:[0,1,0]
	v_pk_fma_f32 v[16:17], v[82:83], v[54:55], v[16:17] op_sel:[0,1,0]
	v_add_u32_e32 v40, 0x1030, v35
	v_add_u32_e32 v42, 0x2030, v35
	v_add_u32_e32 v44, 0x3030, v35
	v_add_u32_e32 v46, 0x4030, v35
	v_add_u32_e32 v48, 0x5030, v35
	v_add_u32_e32 v50, 0x6030, v35
	v_add_u32_e32 v52, 0x7030, v35
	v_add_u32_e32 v54, 0x8030, v35
	ds_read2_b32 v[38:39], v35 offset0:12 offset1:13
	ds_read2_b32 v[40:41], v40 offset1:1
	ds_read2_b32 v[42:43], v42 offset1:1
	ds_read2_b32 v[44:45], v44 offset1:1
	ds_read2_b32 v[46:47], v46 offset1:1
	ds_read2_b32 v[48:49], v48 offset1:1
	ds_read2_b32 v[50:51], v50 offset1:1
	ds_read2_b32 v[52:53], v52 offset1:1
	ds_read2_b32 v[54:55], v54 offset1:1
	s_waitcnt vmcnt(3) lgkmcnt(8)
	v_pk_fma_f32 v[32:33], v[84:85], v[38:39], v[32:33] op_sel_hi:[1,0,1]
	s_waitcnt lgkmcnt(7)
	v_pk_fma_f32 v[30:31], v[84:85], v[40:41], v[30:31] op_sel_hi:[1,0,1]
	s_waitcnt lgkmcnt(6)
	v_pk_fma_f32 v[28:29], v[84:85], v[42:43], v[28:29] op_sel_hi:[1,0,1]
	s_waitcnt lgkmcnt(5)
	v_pk_fma_f32 v[26:27], v[84:85], v[44:45], v[26:27] op_sel_hi:[1,0,1]
	s_waitcnt lgkmcnt(4)
	v_pk_fma_f32 v[24:25], v[84:85], v[46:47], v[24:25] op_sel_hi:[1,0,1]
	s_waitcnt lgkmcnt(3)
	v_pk_fma_f32 v[22:23], v[84:85], v[48:49], v[22:23] op_sel_hi:[1,0,1]
	s_waitcnt lgkmcnt(2)
	v_pk_fma_f32 v[20:21], v[84:85], v[50:51], v[20:21] op_sel_hi:[1,0,1]
	s_waitcnt lgkmcnt(1)
	v_pk_fma_f32 v[18:19], v[84:85], v[52:53], v[18:19] op_sel_hi:[1,0,1]
	s_waitcnt lgkmcnt(0)
	v_pk_fma_f32 v[16:17], v[84:85], v[54:55], v[16:17] op_sel_hi:[1,0,1]
	s_waitcnt vmcnt(2)
	v_pk_fma_f32 v[32:33], v[86:87], v[38:39], v[32:33] op_sel:[0,1,0]
	v_pk_fma_f32 v[30:31], v[86:87], v[40:41], v[30:31] op_sel:[0,1,0]
	v_pk_fma_f32 v[28:29], v[86:87], v[42:43], v[28:29] op_sel:[0,1,0]
	v_pk_fma_f32 v[26:27], v[86:87], v[44:45], v[26:27] op_sel:[0,1,0]
	v_pk_fma_f32 v[24:25], v[86:87], v[46:47], v[24:25] op_sel:[0,1,0]
	v_pk_fma_f32 v[22:23], v[86:87], v[48:49], v[22:23] op_sel:[0,1,0]
	v_pk_fma_f32 v[20:21], v[86:87], v[50:51], v[20:21] op_sel:[0,1,0]
	v_pk_fma_f32 v[18:19], v[86:87], v[52:53], v[18:19] op_sel:[0,1,0]
	v_pk_fma_f32 v[16:17], v[86:87], v[54:55], v[16:17] op_sel:[0,1,0]
	v_add_u32_e32 v40, 0x1038, v35
	v_add_u32_e32 v42, 0x2038, v35
	v_add_u32_e32 v44, 0x3038, v35
	v_add_u32_e32 v46, 0x4038, v35
	v_add_u32_e32 v48, 0x5038, v35
	v_add_u32_e32 v50, 0x6038, v35
	v_add_u32_e32 v52, 0x7038, v35
	v_add_u32_e32 v54, 0x8038, v35
	ds_read2_b32 v[38:39], v35 offset0:14 offset1:15
	ds_read2_b32 v[40:41], v40 offset1:1
	ds_read2_b32 v[42:43], v42 offset1:1
	ds_read2_b32 v[44:45], v44 offset1:1
	ds_read2_b32 v[46:47], v46 offset1:1
	ds_read2_b32 v[48:49], v48 offset1:1
	ds_read2_b32 v[50:51], v50 offset1:1
	ds_read2_b32 v[52:53], v52 offset1:1
	ds_read2_b32 v[54:55], v54 offset1:1
	v_add_u32_e32 v35, 64, v35
	s_waitcnt vmcnt(1) lgkmcnt(8)
	v_pk_fma_f32 v[32:33], v[88:89], v[38:39], v[32:33] op_sel_hi:[1,0,1]
	s_waitcnt lgkmcnt(7)
	v_pk_fma_f32 v[30:31], v[88:89], v[40:41], v[30:31] op_sel_hi:[1,0,1]
	s_waitcnt lgkmcnt(6)
	v_pk_fma_f32 v[28:29], v[88:89], v[42:43], v[28:29] op_sel_hi:[1,0,1]
	s_waitcnt lgkmcnt(5)
	v_pk_fma_f32 v[26:27], v[88:89], v[44:45], v[26:27] op_sel_hi:[1,0,1]
	s_waitcnt lgkmcnt(4)
	v_pk_fma_f32 v[24:25], v[88:89], v[46:47], v[24:25] op_sel_hi:[1,0,1]
	s_waitcnt lgkmcnt(3)
	v_pk_fma_f32 v[22:23], v[88:89], v[48:49], v[22:23] op_sel_hi:[1,0,1]
	s_waitcnt lgkmcnt(2)
	v_pk_fma_f32 v[20:21], v[88:89], v[50:51], v[20:21] op_sel_hi:[1,0,1]
	s_waitcnt lgkmcnt(1)
	v_pk_fma_f32 v[18:19], v[88:89], v[52:53], v[18:19] op_sel_hi:[1,0,1]
	s_waitcnt lgkmcnt(0)
	v_pk_fma_f32 v[16:17], v[88:89], v[54:55], v[16:17] op_sel_hi:[1,0,1]
	s_waitcnt vmcnt(0)
	v_pk_fma_f32 v[32:33], v[90:91], v[38:39], v[32:33] op_sel:[0,1,0]
	v_pk_fma_f32 v[30:31], v[90:91], v[40:41], v[30:31] op_sel:[0,1,0]
	v_pk_fma_f32 v[28:29], v[90:91], v[42:43], v[28:29] op_sel:[0,1,0]
	v_pk_fma_f32 v[26:27], v[90:91], v[44:45], v[26:27] op_sel:[0,1,0]
	v_pk_fma_f32 v[24:25], v[90:91], v[46:47], v[24:25] op_sel:[0,1,0]
	v_pk_fma_f32 v[22:23], v[90:91], v[48:49], v[22:23] op_sel:[0,1,0]
	v_pk_fma_f32 v[20:21], v[90:91], v[50:51], v[20:21] op_sel:[0,1,0]
	v_pk_fma_f32 v[18:19], v[90:91], v[52:53], v[18:19] op_sel:[0,1,0]
	v_pk_fma_f32 v[16:17], v[90:91], v[54:55], v[16:17] op_sel:[0,1,0]
	ds_write2st64_b64 v7, v[32:33], v[30:31] offset0:72 offset1:73
	ds_write2st64_b64 v7, v[28:29], v[26:27] offset0:74 offset1:75
	ds_write2st64_b64 v7, v[24:25], v[22:23] offset0:76 offset1:77
	ds_write2st64_b64 v7, v[20:21], v[18:19] offset0:78 offset1:79
	ds_write_b64 v7, v[16:17] offset:40960
	s_waitcnt lgkmcnt(0)
	s_barrier
	s_and_saveexec_b64 s[6:7], vcc
	s_cbranch_execz .LBB0_48
	s_load_dwordx2 s[0:1], s[76:77], 0x38
	s_mul_i32 s10, s4, 0x6000
	s_mul_hi_i32 s8, s4, 0x6000
	s_mul_hi_i32 s15, s4, 9
	s_mul_i32 s14, s4, 9
	s_waitcnt lgkmcnt(0)
	s_add_u32 s0, s0, s10
	s_addc_u32 s1, s1, s8
	s_add_u32 s0, s0, s2
	s_addc_u32 s1, s1, s3
	v_lshl_add_u64 v[12:13], s[0:1], 0, v[0:1]
	v_lshl_add_u64 v[14:15], v[8:9], 0, s[2:3]
	s_mov_b64 s[2:3], 0
	v_mov_b32_e32 v16, v200
